# P8: gate tile loaded by per-wave LDS-DMA rows (32 async dword loads per pass) instead of 8 serialized load/wait/ds_write
# speedup vs baseline: 1.0607x; 1.0142x over previous
.LBB0_1314:
	v_cndmask_b32_e64 v204, 1.0, -1.0, s[30:31]
	v_add_u32_e32 v247, 0x2000, v219
	s_or_b64 s[38:39], s[30:31], s[6:7]
	v_readfirstlane_b32 s46, v202
	v_readfirstlane_b32 s47, v203
	v_lshrrev_b32_e32 v192, 6, v208
	v_and_b32_e32 v193, 63, v208
	v_readfirstlane_b32 s50, v192
	v_lshlrev_b32_e32 v193, 2, v193
	v_readfirstlane_b32 s51, v228
	s_mul_i32 s53, s50, 28
	s_lshl_b32 s50, s50, 5
	s_add_u32 s51, s51, s53
	s_mul_i32 s52, s50, 0x110
	s_add_u32 s52, s52, 0x10800
	s_cmp_lg_u32 s30, 0
	s_cbranch_scc0 .Lp8_pass1
	s_lshl_b32 s53, s51, 12
	s_add_u32 s48, s46, s53
	s_addc_u32 s49, s47, 0
	s_add_u32 m0, s52, 0x0
	s_nop 0
	global_load_lds_dword v193, s[48:49]
	s_add_u32 m0, s52, 0x110
	s_add_u32 s48, s48, 0x1000
	s_addc_u32 s49, s49, 0
	global_load_lds_dword v193, s[48:49]
	s_add_u32 m0, s52, 0x220
	s_add_u32 s48, s48, 0x1000
	s_addc_u32 s49, s49, 0
	global_load_lds_dword v193, s[48:49]
	s_add_u32 m0, s52, 0x330
	s_add_u32 s48, s48, 0x1000
	s_addc_u32 s49, s49, 0
	global_load_lds_dword v193, s[48:49]
	s_add_u32 m0, s52, 0x440
	s_add_u32 s48, s48, 0x1000
	s_addc_u32 s49, s49, 0
	global_load_lds_dword v193, s[48:49]
	s_add_u32 m0, s52, 0x550
	s_add_u32 s48, s48, 0x1000
	s_addc_u32 s49, s49, 0
	global_load_lds_dword v193, s[48:49]
	s_add_u32 m0, s52, 0x660
	s_add_u32 s48, s48, 0x1000
	s_addc_u32 s49, s49, 0
	global_load_lds_dword v193, s[48:49]
	s_add_u32 m0, s52, 0x770
	s_add_u32 s48, s48, 0x1000
	s_addc_u32 s49, s49, 0
	global_load_lds_dword v193, s[48:49]
	s_add_u32 m0, s52, 0x880
	s_add_u32 s48, s48, 0x1000
	s_addc_u32 s49, s49, 0
	global_load_lds_dword v193, s[48:49]
	s_add_u32 m0, s52, 0x990
	s_add_u32 s48, s48, 0x1000
	s_addc_u32 s49, s49, 0
	global_load_lds_dword v193, s[48:49]
	s_add_u32 m0, s52, 0xaa0
	s_add_u32 s48, s48, 0x1000
	s_addc_u32 s49, s49, 0
	global_load_lds_dword v193, s[48:49]
	s_add_u32 m0, s52, 0xbb0
	s_add_u32 s48, s48, 0x1000
	s_addc_u32 s49, s49, 0
	global_load_lds_dword v193, s[48:49]
	s_add_u32 m0, s52, 0xcc0
	s_add_u32 s48, s48, 0x1000
	s_addc_u32 s49, s49, 0
	global_load_lds_dword v193, s[48:49]
	s_add_u32 m0, s52, 0xdd0
	s_add_u32 s48, s48, 0x1000
	s_addc_u32 s49, s49, 0
	global_load_lds_dword v193, s[48:49]
	s_add_u32 m0, s52, 0xee0
	s_add_u32 s48, s48, 0x1000
	s_addc_u32 s49, s49, 0
	global_load_lds_dword v193, s[48:49]
	s_add_u32 m0, s52, 0xff0
	s_add_u32 s48, s48, 0x1000
	s_addc_u32 s49, s49, 0
	global_load_lds_dword v193, s[48:49]
	s_add_u32 m0, s52, 0x1100
	s_add_u32 s48, s48, 0x1000
	s_addc_u32 s49, s49, 0
	global_load_lds_dword v193, s[48:49]
	s_add_u32 m0, s52, 0x1210
	s_add_u32 s48, s48, 0x1000
	s_addc_u32 s49, s49, 0
	global_load_lds_dword v193, s[48:49]
	s_add_u32 m0, s52, 0x1320
	s_add_u32 s48, s48, 0x1000
	s_addc_u32 s49, s49, 0
	global_load_lds_dword v193, s[48:49]
	s_add_u32 m0, s52, 0x1430
	s_add_u32 s48, s48, 0x1000
	s_addc_u32 s49, s49, 0
	global_load_lds_dword v193, s[48:49]
	s_add_u32 m0, s52, 0x1540
	s_add_u32 s48, s48, 0x1000
	s_addc_u32 s49, s49, 0
	global_load_lds_dword v193, s[48:49]
	s_add_u32 m0, s52, 0x1650
	s_add_u32 s48, s48, 0x1000
	s_addc_u32 s49, s49, 0
	global_load_lds_dword v193, s[48:49]
	s_add_u32 m0, s52, 0x1760
	s_add_u32 s48, s48, 0x1000
	s_addc_u32 s49, s49, 0
	global_load_lds_dword v193, s[48:49]
	s_add_u32 m0, s52, 0x1870
	s_add_u32 s48, s48, 0x1000
	s_addc_u32 s49, s49, 0
	global_load_lds_dword v193, s[48:49]
	s_add_u32 m0, s52, 0x1980
	s_add_u32 s48, s48, 0x1000
	s_addc_u32 s49, s49, 0
	global_load_lds_dword v193, s[48:49]
	s_add_u32 m0, s52, 0x1a90
	s_add_u32 s48, s48, 0x1000
	s_addc_u32 s49, s49, 0
	global_load_lds_dword v193, s[48:49]
	s_add_u32 m0, s52, 0x1ba0
	s_add_u32 s48, s48, 0x1000
	s_addc_u32 s49, s49, 0
	global_load_lds_dword v193, s[48:49]
	s_add_u32 m0, s52, 0x1cb0
	s_add_u32 s48, s48, 0x1000
	s_addc_u32 s49, s49, 0
	global_load_lds_dword v193, s[48:49]
	s_add_u32 m0, s52, 0x1dc0
	s_add_u32 s48, s48, 0x1000
	s_addc_u32 s49, s49, 0
	global_load_lds_dword v193, s[48:49]
	s_add_u32 m0, s52, 0x1ed0
	s_add_u32 s48, s48, 0x1000
	s_addc_u32 s49, s49, 0
	global_load_lds_dword v193, s[48:49]
	s_add_u32 m0, s52, 0x1fe0
	s_add_u32 s48, s48, 0x1000
	s_addc_u32 s49, s49, 0
	global_load_lds_dword v193, s[48:49]
	s_add_u32 m0, s52, 0x20f0
	s_add_u32 s48, s48, 0x1000
	s_addc_u32 s49, s49, 0
	global_load_lds_dword v193, s[48:49]
	s_branch .Lp8_dma_done
.Lp8_pass1:
	s_sub_u32 s53, 0x800, s51
	s_cmp_eq_u32 s51, 0
	s_cselect_b32 s48, 0, s53
	s_lshl_b32 s48, s48, 12
	s_add_u32 s48, s46, s48
	s_addc_u32 s49, s47, 0
	s_add_u32 m0, s52, 0x0
	s_nop 0
	global_load_lds_dword v193, s[48:49]
	s_lshl_b32 s53, s53, 12
	s_add_u32 s48, s46, s53
	s_addc_u32 s49, s47, 0
	s_add_u32 m0, s52, 0x110
	s_sub_u32 s48, s48, 0x1000
	s_subb_u32 s49, s49, 0
	global_load_lds_dword v193, s[48:49]
	s_add_u32 m0, s52, 0x220
	s_sub_u32 s48, s48, 0x1000
	s_subb_u32 s49, s49, 0
	global_load_lds_dword v193, s[48:49]
	s_add_u32 m0, s52, 0x330
	s_sub_u32 s48, s48, 0x1000
	s_subb_u32 s49, s49, 0
	global_load_lds_dword v193, s[48:49]
	s_add_u32 m0, s52, 0x440
	s_sub_u32 s48, s48, 0x1000
	s_subb_u32 s49, s49, 0
	global_load_lds_dword v193, s[48:49]
	s_add_u32 m0, s52, 0x550
	s_sub_u32 s48, s48, 0x1000
	s_subb_u32 s49, s49, 0
	global_load_lds_dword v193, s[48:49]
	s_add_u32 m0, s52, 0x660
	s_sub_u32 s48, s48, 0x1000
	s_subb_u32 s49, s49, 0
	global_load_lds_dword v193, s[48:49]
	s_add_u32 m0, s52, 0x770
	s_sub_u32 s48, s48, 0x1000
	s_subb_u32 s49, s49, 0
	global_load_lds_dword v193, s[48:49]
	s_add_u32 m0, s52, 0x880
	s_sub_u32 s48, s48, 0x1000
	s_subb_u32 s49, s49, 0
	global_load_lds_dword v193, s[48:49]
	s_add_u32 m0, s52, 0x990
	s_sub_u32 s48, s48, 0x1000
	s_subb_u32 s49, s49, 0
	global_load_lds_dword v193, s[48:49]
	s_add_u32 m0, s52, 0xaa0
	s_sub_u32 s48, s48, 0x1000
	s_subb_u32 s49, s49, 0
	global_load_lds_dword v193, s[48:49]
	s_add_u32 m0, s52, 0xbb0
	s_sub_u32 s48, s48, 0x1000
	s_subb_u32 s49, s49, 0
	global_load_lds_dword v193, s[48:49]
	s_add_u32 m0, s52, 0xcc0
	s_sub_u32 s48, s48, 0x1000
	s_subb_u32 s49, s49, 0
	global_load_lds_dword v193, s[48:49]
	s_add_u32 m0, s52, 0xdd0
	s_sub_u32 s48, s48, 0x1000
	s_subb_u32 s49, s49, 0
	global_load_lds_dword v193, s[48:49]
	s_add_u32 m0, s52, 0xee0
	s_sub_u32 s48, s48, 0x1000
	s_subb_u32 s49, s49, 0
	global_load_lds_dword v193, s[48:49]
	s_add_u32 m0, s52, 0xff0
	s_sub_u32 s48, s48, 0x1000
	s_subb_u32 s49, s49, 0
	global_load_lds_dword v193, s[48:49]
	s_add_u32 m0, s52, 0x1100
	s_sub_u32 s48, s48, 0x1000
	s_subb_u32 s49, s49, 0
	global_load_lds_dword v193, s[48:49]
	s_add_u32 m0, s52, 0x1210
	s_sub_u32 s48, s48, 0x1000
	s_subb_u32 s49, s49, 0
	global_load_lds_dword v193, s[48:49]
	s_add_u32 m0, s52, 0x1320
	s_sub_u32 s48, s48, 0x1000
	s_subb_u32 s49, s49, 0
	global_load_lds_dword v193, s[48:49]
	s_add_u32 m0, s52, 0x1430
	s_sub_u32 s48, s48, 0x1000
	s_subb_u32 s49, s49, 0
	global_load_lds_dword v193, s[48:49]
	s_add_u32 m0, s52, 0x1540
	s_sub_u32 s48, s48, 0x1000
	s_subb_u32 s49, s49, 0
	global_load_lds_dword v193, s[48:49]
	s_add_u32 m0, s52, 0x1650
	s_sub_u32 s48, s48, 0x1000
	s_subb_u32 s49, s49, 0
	global_load_lds_dword v193, s[48:49]
	s_add_u32 m0, s52, 0x1760
	s_sub_u32 s48, s48, 0x1000
	s_subb_u32 s49, s49, 0
	global_load_lds_dword v193, s[48:49]
	s_add_u32 m0, s52, 0x1870
	s_sub_u32 s48, s48, 0x1000
	s_subb_u32 s49, s49, 0
	global_load_lds_dword v193, s[48:49]
	s_add_u32 m0, s52, 0x1980
	s_sub_u32 s48, s48, 0x1000
	s_subb_u32 s49, s49, 0
	global_load_lds_dword v193, s[48:49]
	s_add_u32 m0, s52, 0x1a90
	s_sub_u32 s48, s48, 0x1000
	s_subb_u32 s49, s49, 0
	global_load_lds_dword v193, s[48:49]
	s_add_u32 m0, s52, 0x1ba0
	s_sub_u32 s48, s48, 0x1000
	s_subb_u32 s49, s49, 0
	global_load_lds_dword v193, s[48:49]
	s_add_u32 m0, s52, 0x1cb0
	s_sub_u32 s48, s48, 0x1000
	s_subb_u32 s49, s49, 0
	global_load_lds_dword v193, s[48:49]
	s_add_u32 m0, s52, 0x1dc0
	s_sub_u32 s48, s48, 0x1000
	s_subb_u32 s49, s49, 0
	global_load_lds_dword v193, s[48:49]
	s_add_u32 m0, s52, 0x1ed0
	s_sub_u32 s48, s48, 0x1000
	s_subb_u32 s49, s49, 0
	global_load_lds_dword v193, s[48:49]
	s_add_u32 m0, s52, 0x1fe0
	s_sub_u32 s48, s48, 0x1000
	s_subb_u32 s49, s49, 0
	global_load_lds_dword v193, s[48:49]
	s_add_u32 m0, s52, 0x20f0
	s_sub_u32 s48, s48, 0x1000
	s_subb_u32 s49, s49, 0
	global_load_lds_dword v193, s[48:49]
.Lp8_dma_done:
	s_waitcnt vmcnt(0)
	v_pk_fma_f32 v[192:193], v[204:205], v[64:65], v[0:1] op_sel_hi:[0,1,1]
	s_waitcnt lgkmcnt(0)
	s_barrier
	v_pk_mul_f32 v[206:207], v[192:193], s[2:3] op_sel_hi:[1,0]
	ds_read2_b64 v[248:251], v219 offset1:2
	ds_read2_b64 v[192:195], v219 offset0:4 offset1:6
	s_waitcnt lgkmcnt(1)
	v_lshlrev_b32_e32 v252, 16, v248
	v_and_b32_e32 v253, 0xffff0000, v248
	v_pk_mul_f32 v[206:207], v[206:207], v[252:253]
	v_pk_fma_f32 v[252:253], v[204:205], v[66:67], v[2:3] op_sel_hi:[0,1,1]
	v_pk_mul_f32 v[252:253], v[252:253], s[2:3] op_sel_hi:[1,0]
	v_lshlrev_b32_e32 v248, 16, v249
	v_and_b32_e32 v249, 0xffff0000, v249
	v_pk_mul_f32 v[248:249], v[252:253], v[248:249]
	v_cvt_pk_bf16_f32 v206, v206, v207
	v_cvt_pk_bf16_f32 v207, v248, v249
	v_pk_fma_f32 v[248:249], v[204:205], v[68:69], v[4:5] op_sel_hi:[0,1,1]
	v_pk_mul_f32 v[248:249], v[248:249], s[2:3] op_sel_hi:[1,0]
	v_lshlrev_b32_e32 v252, 16, v250
	v_and_b32_e32 v253, 0xffff0000, v250
	v_pk_mul_f32 v[248:249], v[248:249], v[252:253]
	v_pk_fma_f32 v[252:253], v[204:205], v[70:71], v[6:7] op_sel_hi:[0,1,1]
	v_pk_mul_f32 v[252:253], v[252:253], s[2:3] op_sel_hi:[1,0]
	v_lshlrev_b32_e32 v250, 16, v251
	v_and_b32_e32 v251, 0xffff0000, v251
	v_pk_mul_f32 v[250:251], v[252:253], v[250:251]
	v_cvt_pk_bf16_f32 v248, v248, v249
	v_cvt_pk_bf16_f32 v249, v250, v251
	ds_write2_b64 v219, v[206:207], v[248:249] offset1:2
	v_pk_fma_f32 v[206:207], v[204:205], v[72:73], v[8:9] op_sel_hi:[0,1,1]
	v_pk_mul_f32 v[206:207], v[206:207], s[2:3] op_sel_hi:[1,0]
	s_waitcnt lgkmcnt(1)
	v_lshlrev_b32_e32 v248, 16, v192
	v_and_b32_e32 v249, 0xffff0000, v192
	v_pk_mul_f32 v[206:207], v[206:207], v[248:249]
	v_lshlrev_b32_e32 v248, 16, v193
	v_cvt_pk_bf16_f32 v192, v206, v207
	v_pk_fma_f32 v[206:207], v[204:205], v[74:75], v[10:11] op_sel_hi:[0,1,1]
	v_pk_mul_f32 v[206:207], v[206:207], s[2:3] op_sel_hi:[1,0]
	v_and_b32_e32 v249, 0xffff0000, v193
	v_pk_mul_f32 v[206:207], v[206:207], v[248:249]
	v_lshlrev_b32_e32 v248, 16, v194
	v_cvt_pk_bf16_f32 v193, v206, v207
	v_pk_fma_f32 v[206:207], v[204:205], v[76:77], v[12:13] op_sel_hi:[0,1,1]
	v_pk_mul_f32 v[206:207], v[206:207], s[2:3] op_sel_hi:[1,0]
	v_and_b32_e32 v249, 0xffff0000, v194
	v_pk_mul_f32 v[206:207], v[206:207], v[248:249]
	v_lshlrev_b32_e32 v248, 16, v195
	v_cvt_pk_bf16_f32 v194, v206, v207
	v_pk_fma_f32 v[206:207], v[204:205], v[78:79], v[14:15] op_sel_hi:[0,1,1]
	v_pk_mul_f32 v[206:207], v[206:207], s[2:3] op_sel_hi:[1,0]
	v_and_b32_e32 v249, 0xffff0000, v195
	v_pk_mul_f32 v[206:207], v[206:207], v[248:249]
	s_nop 0
	v_cvt_pk_bf16_f32 v195, v206, v207
	ds_write2_b64 v219, v[192:193], v[194:195] offset0:4 offset1:6
	ds_read2_b64 v[192:195], v219 offset0:16 offset1:18
	v_pk_fma_f32 v[206:207], v[204:205], v[80:81], v[16:17] op_sel_hi:[0,1,1]
	v_pk_mul_f32 v[206:207], v[206:207], s[2:3] op_sel_hi:[1,0]
	s_waitcnt lgkmcnt(0)
	v_lshlrev_b32_e32 v248, 16, v192
	v_and_b32_e32 v249, 0xffff0000, v192
	v_pk_mul_f32 v[206:207], v[206:207], v[248:249]
	v_lshlrev_b32_e32 v248, 16, v193
	v_cvt_pk_bf16_f32 v192, v206, v207
	v_pk_fma_f32 v[206:207], v[204:205], v[82:83], v[18:19] op_sel_hi:[0,1,1]
	v_pk_mul_f32 v[206:207], v[206:207], s[2:3] op_sel_hi:[1,0]
	v_and_b32_e32 v249, 0xffff0000, v193
	v_pk_mul_f32 v[206:207], v[206:207], v[248:249]
	v_lshlrev_b32_e32 v248, 16, v194
	v_cvt_pk_bf16_f32 v193, v206, v207
	v_pk_fma_f32 v[206:207], v[204:205], v[84:85], v[20:21] op_sel_hi:[0,1,1]
	v_pk_mul_f32 v[206:207], v[206:207], s[2:3] op_sel_hi:[1,0]
	v_and_b32_e32 v249, 0xffff0000, v194
	v_pk_mul_f32 v[206:207], v[206:207], v[248:249]
	v_lshlrev_b32_e32 v248, 16, v195
	v_cvt_pk_bf16_f32 v194, v206, v207
	v_pk_fma_f32 v[206:207], v[204:205], v[86:87], v[22:23] op_sel_hi:[0,1,1]
	v_pk_mul_f32 v[206:207], v[206:207], s[2:3] op_sel_hi:[1,0]
	v_and_b32_e32 v249, 0xffff0000, v195
	v_pk_mul_f32 v[206:207], v[206:207], v[248:249]
	s_nop 0
	v_cvt_pk_bf16_f32 v195, v206, v207
	ds_write2_b64 v219, v[192:193], v[194:195] offset0:16 offset1:18
	ds_read2_b64 v[192:195], v219 offset0:20 offset1:22
	v_pk_fma_f32 v[206:207], v[204:205], v[88:89], v[24:25] op_sel_hi:[0,1,1]
	v_pk_mul_f32 v[206:207], v[206:207], s[2:3] op_sel_hi:[1,0]
	s_waitcnt lgkmcnt(0)
	v_lshlrev_b32_e32 v248, 16, v192
	v_and_b32_e32 v249, 0xffff0000, v192
	v_pk_mul_f32 v[206:207], v[206:207], v[248:249]
	v_lshlrev_b32_e32 v248, 16, v193
	v_cvt_pk_bf16_f32 v192, v206, v207
	v_pk_fma_f32 v[206:207], v[204:205], v[90:91], v[26:27] op_sel_hi:[0,1,1]
	v_pk_mul_f32 v[206:207], v[206:207], s[2:3] op_sel_hi:[1,0]
	v_and_b32_e32 v249, 0xffff0000, v193
	v_pk_mul_f32 v[206:207], v[206:207], v[248:249]
	v_lshlrev_b32_e32 v248, 16, v194
	v_cvt_pk_bf16_f32 v193, v206, v207
	v_pk_fma_f32 v[206:207], v[204:205], v[92:93], v[28:29] op_sel_hi:[0,1,1]
	v_pk_mul_f32 v[206:207], v[206:207], s[2:3] op_sel_hi:[1,0]
	v_and_b32_e32 v249, 0xffff0000, v194
	v_pk_mul_f32 v[206:207], v[206:207], v[248:249]
	v_lshlrev_b32_e32 v248, 16, v195
	v_cvt_pk_bf16_f32 v194, v206, v207
	v_pk_fma_f32 v[206:207], v[204:205], v[94:95], v[30:31] op_sel_hi:[0,1,1]
	v_pk_mul_f32 v[206:207], v[206:207], s[2:3] op_sel_hi:[1,0]
	v_and_b32_e32 v249, 0xffff0000, v195
	v_pk_mul_f32 v[206:207], v[206:207], v[248:249]
	s_nop 0
	v_cvt_pk_bf16_f32 v195, v206, v207
	ds_write2_b64 v219, v[192:193], v[194:195] offset0:20 offset1:22
	ds_read2_b64 v[192:195], v247 offset0:64 offset1:66
	v_pk_fma_f32 v[206:207], v[204:205], v[96:97], v[32:33] op_sel_hi:[0,1,1]
	v_pk_mul_f32 v[206:207], v[206:207], s[2:3] op_sel_hi:[1,0]
	s_waitcnt lgkmcnt(0)
	v_lshlrev_b32_e32 v248, 16, v192
	v_and_b32_e32 v249, 0xffff0000, v192
	v_pk_mul_f32 v[206:207], v[206:207], v[248:249]
	v_lshlrev_b32_e32 v248, 16, v193
	v_cvt_pk_bf16_f32 v192, v206, v207
	v_pk_fma_f32 v[206:207], v[204:205], v[98:99], v[34:35] op_sel_hi:[0,1,1]
	v_pk_mul_f32 v[206:207], v[206:207], s[2:3] op_sel_hi:[1,0]
	v_and_b32_e32 v249, 0xffff0000, v193
	v_pk_mul_f32 v[206:207], v[206:207], v[248:249]
	v_lshlrev_b32_e32 v248, 16, v194
	v_cvt_pk_bf16_f32 v193, v206, v207
	v_pk_fma_f32 v[206:207], v[204:205], v[100:101], v[36:37] op_sel_hi:[0,1,1]
	v_pk_mul_f32 v[206:207], v[206:207], s[2:3] op_sel_hi:[1,0]
	v_and_b32_e32 v249, 0xffff0000, v194
	v_pk_mul_f32 v[206:207], v[206:207], v[248:249]
	v_lshlrev_b32_e32 v248, 16, v195
	v_cvt_pk_bf16_f32 v194, v206, v207
	v_pk_fma_f32 v[206:207], v[204:205], v[102:103], v[38:39] op_sel_hi:[0,1,1]
	v_pk_mul_f32 v[206:207], v[206:207], s[2:3] op_sel_hi:[1,0]
	v_and_b32_e32 v249, 0xffff0000, v195
	v_pk_mul_f32 v[206:207], v[206:207], v[248:249]
	s_nop 0
	v_cvt_pk_bf16_f32 v195, v206, v207
	ds_write2_b64 v247, v[192:193], v[194:195] offset0:64 offset1:66
	ds_read2_b64 v[192:195], v247 offset0:68 offset1:70
	v_pk_fma_f32 v[206:207], v[204:205], v[104:105], v[40:41] op_sel_hi:[0,1,1]
	v_pk_mul_f32 v[206:207], v[206:207], s[2:3] op_sel_hi:[1,0]
	s_waitcnt lgkmcnt(0)
	v_lshlrev_b32_e32 v248, 16, v192
	v_and_b32_e32 v249, 0xffff0000, v192
	v_pk_mul_f32 v[206:207], v[206:207], v[248:249]
	v_lshlrev_b32_e32 v248, 16, v193
	v_cvt_pk_bf16_f32 v192, v206, v207
	v_pk_fma_f32 v[206:207], v[204:205], v[106:107], v[42:43] op_sel_hi:[0,1,1]
	v_pk_mul_f32 v[206:207], v[206:207], s[2:3] op_sel_hi:[1,0]
	v_and_b32_e32 v249, 0xffff0000, v193
	v_pk_mul_f32 v[206:207], v[206:207], v[248:249]
	v_lshlrev_b32_e32 v248, 16, v194
	v_cvt_pk_bf16_f32 v193, v206, v207
	v_pk_fma_f32 v[206:207], v[204:205], v[108:109], v[44:45] op_sel_hi:[0,1,1]
	v_pk_mul_f32 v[206:207], v[206:207], s[2:3] op_sel_hi:[1,0]
	v_and_b32_e32 v249, 0xffff0000, v194
	v_pk_mul_f32 v[206:207], v[206:207], v[248:249]
	v_lshlrev_b32_e32 v248, 16, v195
	v_cvt_pk_bf16_f32 v194, v206, v207
	v_pk_fma_f32 v[206:207], v[204:205], v[110:111], v[46:47] op_sel_hi:[0,1,1]
	v_pk_mul_f32 v[206:207], v[206:207], s[2:3] op_sel_hi:[1,0]
	v_and_b32_e32 v249, 0xffff0000, v195
	v_pk_mul_f32 v[206:207], v[206:207], v[248:249]
	s_nop 0
	v_cvt_pk_bf16_f32 v195, v206, v207
	ds_write2_b64 v247, v[192:193], v[194:195] offset0:68 offset1:70
	ds_read2_b64 v[192:195], v247 offset0:80 offset1:82
	v_pk_fma_f32 v[206:207], v[204:205], v[112:113], v[48:49] op_sel_hi:[0,1,1]
	v_pk_mul_f32 v[206:207], v[206:207], s[2:3] op_sel_hi:[1,0]
	s_waitcnt lgkmcnt(0)
	v_lshlrev_b32_e32 v248, 16, v192
	v_and_b32_e32 v249, 0xffff0000, v192
	v_pk_mul_f32 v[206:207], v[206:207], v[248:249]
	v_lshlrev_b32_e32 v248, 16, v193
	v_cvt_pk_bf16_f32 v192, v206, v207
	v_pk_fma_f32 v[206:207], v[204:205], v[114:115], v[50:51] op_sel_hi:[0,1,1]
	v_pk_mul_f32 v[206:207], v[206:207], s[2:3] op_sel_hi:[1,0]
	v_and_b32_e32 v249, 0xffff0000, v193
	v_pk_mul_f32 v[206:207], v[206:207], v[248:249]
	v_lshlrev_b32_e32 v248, 16, v194
	v_cvt_pk_bf16_f32 v193, v206, v207
	v_pk_fma_f32 v[206:207], v[204:205], v[116:117], v[52:53] op_sel_hi:[0,1,1]
	v_pk_mul_f32 v[206:207], v[206:207], s[2:3] op_sel_hi:[1,0]
	v_and_b32_e32 v249, 0xffff0000, v194
	v_pk_mul_f32 v[206:207], v[206:207], v[248:249]
	v_lshlrev_b32_e32 v248, 16, v195
	v_cvt_pk_bf16_f32 v194, v206, v207
	v_pk_fma_f32 v[206:207], v[204:205], v[118:119], v[54:55] op_sel_hi:[0,1,1]
	v_pk_mul_f32 v[206:207], v[206:207], s[2:3] op_sel_hi:[1,0]
	v_and_b32_e32 v249, 0xffff0000, v195
	v_pk_mul_f32 v[206:207], v[206:207], v[248:249]
	s_nop 0
	v_cvt_pk_bf16_f32 v195, v206, v207
	ds_write2_b64 v247, v[192:193], v[194:195] offset0:80 offset1:82
	ds_read2_b64 v[192:195], v247 offset0:84 offset1:86
	v_pk_fma_f32 v[206:207], v[204:205], v[120:121], v[56:57] op_sel_hi:[0,1,1]
	v_pk_mul_f32 v[206:207], v[206:207], s[2:3] op_sel_hi:[1,0]
	s_waitcnt lgkmcnt(0)
	v_lshlrev_b32_e32 v248, 16, v192
	v_and_b32_e32 v249, 0xffff0000, v192
	v_pk_mul_f32 v[206:207], v[206:207], v[248:249]
	v_lshlrev_b32_e32 v248, 16, v193
	v_cvt_pk_bf16_f32 v192, v206, v207
	v_pk_fma_f32 v[206:207], v[204:205], v[122:123], v[58:59] op_sel_hi:[0,1,1]
	v_pk_mul_f32 v[206:207], v[206:207], s[2:3] op_sel_hi:[1,0]
	v_and_b32_e32 v249, 0xffff0000, v193
	v_pk_mul_f32 v[206:207], v[206:207], v[248:249]
	v_lshlrev_b32_e32 v248, 16, v194
	v_cvt_pk_bf16_f32 v193, v206, v207
	v_pk_fma_f32 v[206:207], v[204:205], v[124:125], v[60:61] op_sel_hi:[0,1,1]
	v_pk_mul_f32 v[206:207], v[206:207], s[2:3] op_sel_hi:[1,0]
	v_and_b32_e32 v249, 0xffff0000, v194
	v_pk_mul_f32 v[206:207], v[206:207], v[248:249]
	v_pk_fma_f32 v[204:205], v[204:205], v[126:127], v[62:63] op_sel_hi:[0,1,1]
	v_cvt_pk_bf16_f32 v194, v206, v207
	v_pk_mul_f32 v[204:205], v[204:205], s[2:3] op_sel_hi:[1,0]
	v_lshlrev_b32_e32 v206, 16, v195
	v_and_b32_e32 v207, 0xffff0000, v195
	v_pk_mul_f32 v[204:205], v[204:205], v[206:207]
	s_nop 0
	v_cvt_pk_bf16_f32 v195, v204, v205
	ds_write2_b64 v247, v[192:193], v[194:195] offset0:84 offset1:86
	s_waitcnt lgkmcnt(0)
	s_barrier
	s_and_saveexec_b64 s[34:35], s[38:39]
	s_cbranch_execz .LBB0_1322
	ds_read_b128 v[192:195], v220
	v_cndmask_b32_e64 v204, v229, v228, s[30:31]
	v_ashrrev_i32_e32 v205, 31, v204
	v_lshlrev_b64 v[204:205], 12, v[204:205]
	v_lshl_add_u64 v[204:205], v[202:203], 0, v[204:205]
	s_waitcnt lgkmcnt(0)
	global_store_dwordx4 v[204:205], v[192:195], off
	s_or_b64 exec, exec, s[34:35]
	s_or_b64 s[38:39], s[30:31], s[8:9]
	s_and_saveexec_b64 s[34:35], s[38:39]
	s_cbranch_execnz .LBB0_1323
